# out-proj round 0 (256 tiles) executed by idle blocks 96..255 during the scan phase; r16b relocated to ws+242MiB; phase 4 runs round 1 only
# baseline (speedup 1.0000x reference)
.LBB0_284:
	s_waitcnt vmcnt(0) lgkmcnt(0)
	s_barrier
	v_readlane_b32 s0, v254, 0
	v_readlane_b32 s1, v254, 1
	v_readlane_b32 s8, v254, 45
	v_readlane_b32 s9, v254, 46
	s_mov_b64 s[2:3], exec
	s_and_b64 s[0:1], s[2:3], s[0:1]
	s_mov_b64 exec, s[0:1]
	s_cbranch_execz .Lemb_s1
	s_add_u32 s8, s8, 0x1e388000
	s_addc_u32 s9, s9, 0
	buffer_wbl2 sc1
	s_waitcnt vmcnt(0)
	v_mov_b32_e32 v0, 0
	v_mov_b32_e32 v1, 1
	global_atomic_add v0, v1, s[8:9]
.Lemb_s1:
	s_mov_b64 exec, s[2:3]
	v_lshlrev_b32_e32 v2, 1, v113
	v_lshrrev_b32_e32 v3, 5, v186
	v_readlane_b32 s0, v254, 45
	v_and_b32_e32 v2, 24, v2
	v_and_b32_e32 v3, 4, v3
	v_bfe_u32 v4, v186, 2, 2
	s_add_u32 s26, s0, 0x2400000
	v_lshlrev_b32_e32 v0, 4, v186
	v_and_b32_e32 v1, 32, v186
	v_bfe_u32 v145, v186, 2, 4
	v_or3_b32 v2, v3, v4, v2
	v_lshrrev_b32_e32 v3, 3, v186
	s_movk_i32 s0, 0x70
	v_bitop3_b32 v143, v0, v1, 48 bitop3:0x6c
	v_and_b32_e32 v144, 64, v186
	v_and_or_b32 v4, v3, s0, v145
	s_movk_i32 s0, 0x60
	v_add_u32_e32 v146, 0x2000, v0
	v_or_b32_e32 v1, v143, v144
	v_and_or_b32 v3, v3, s0, v2
	v_lshrrev_b32_e32 v0, 7, v146
	s_movk_i32 s0, 0xf0
	v_lshl_or_b32 v130, v3, 11, v1
	v_and_or_b32 v3, v0, s0, v145
	s_movk_i32 s0, 0xe0
	v_and_or_b32 v0, v0, s0, v2
	v_readlane_b32 s1, v254, 46
	v_lshl_or_b32 v134, v0, 11, v1
	v_lshrrev_b32_e32 v0, 1, v186
	s_addc_u32 s27, s1, 0
	v_and_b32_e32 v147, 24, v0
	v_lshlrev_b32_e32 v0, 6, v186
	v_lshl_or_b32 v128, v4, 11, v1
	v_lshl_or_b32 v132, v3, 11, v1
	v_lshlrev_b32_e32 v148, 1, v147
	v_and_b32_e32 v0, 0x3c0, v0
	v_and_b32_e32 v1, 32, v112
	s_cmpk_lt_i32 s93, 0x60
	v_readfirstlane_b32 s8, v186
	s_cselect_b64 s[0:1], -1, 0
	s_cmpk_gt_i32 s93, 0x5f
	v_bitop3_b32 v149, v148, v1, v0 bitop3:0x36
	v_readlane_b32 s2, v254, 47
	v_readlane_b32 s3, v254, 48
	s_barrier
	s_cbranch_scc1 .LBB0_304
	v_readlane_b32 s4, v254, 45
	v_readlane_b32 s5, v254, 46
	s_add_u32 s28, s4, 0xc00000
	s_addc_u32 s29, s5, 0
	s_lshl_b32 s3, s93, 2
	s_lshr_b32 s2, s57, 3
	s_and_b32 s3, s3, 28
	s_add_i32 s3, s3, s2
	s_lshr_b32 s2, s3, 2
	v_readlane_b32 s6, v254, 47
	v_readlane_b32 s7, v254, 48
	s_and_b32 s2, s2, 0xffffff8
	s_and_b32 s4, s3, 7
	s_lshr_b32 s6, s8, 6
	s_or_b32 s2, s2, s4
	s_bfe_u32 s7, s3, 0x20003
	s_mov_b32 s3, 0
	s_lshr_b32 s9, s8, 8
	s_lshl_b32 s30, s6, 10
	s_lshl_b64 s[4:5], s[2:3], 19
	s_lshl_b32 s10, s7, 19
	s_add_u32 s22, s28, s10
	s_addc_u32 s23, s29, 0
	s_add_i32 s31, s30, 0
	s_add_i32 m0, s31, 0x10000
	v_mov_b32_e32 v131, 0
	global_load_lds_dwordx4 v130, s[22:23]
	s_add_i32 m0, s31, 0x12000
	s_add_u32 s10, s22, 0x40000
	global_load_lds_dwordx4 v134, s[22:23]
	s_addc_u32 s11, s23, 0
	s_add_i32 m0, s31, 0x14000
	v_mov_b32_e32 v135, v131
	global_load_lds_dwordx4 v130, s[10:11]
	s_add_i32 m0, s31, 0x16000
	s_add_u32 s20, s26, s4
	s_addc_u32 s21, s27, s5
	s_add_i32 s36, s31, 0x2000
	global_load_lds_dwordx4 v134, s[10:11]
	s_mov_b32 m0, s31
	s_add_u32 s4, s20, 0x40000
	global_load_lds_dwordx4 v128, s[20:21]
	s_mov_b32 m0, s36
	s_addc_u32 s5, s21, 0
	s_add_i32 s37, s31, 0x4000
	global_load_lds_dwordx4 v132, s[20:21]
	s_mov_b32 m0, s37
	s_add_i32 s38, s31, 0x6000
	global_load_lds_dwordx4 v128, s[4:5]
	s_mov_b32 m0, s38
	v_mov_b32_e32 v129, v131
	global_load_lds_dwordx4 v132, s[4:5]
	v_mov_b32_e32 v133, v131
	s_cmp_eq_u32 s9, 1
	v_lshl_add_u64 v[6:7], s[22:23], 0, v[130:131]
	v_lshl_add_u64 v[2:3], s[22:23], 0, v[134:135]
	v_lshl_add_u64 v[0:1], s[20:21], 0, v[128:129]
	s_cselect_b64 s[4:5], -1, 0
	s_cmp_lg_u32 s9, 1
	v_lshl_add_u64 v[4:5], s[20:21], 0, v[132:133]
	s_cbranch_scc1 .LBB0_287
	s_barrier

.LBB0_324:
	v_readlane_b32 s68, v254, 45
	v_readlane_b32 s69, v254, 46
	v_readlane_b32 s70, v254, 47
	v_readlane_b32 s71, v254, 48
	s_cmpk_lt_u32 s93, 0x60
	s_cbranch_scc1 .Lemb_done
	v_readlane_b32 s0, v254, 0
	v_readlane_b32 s1, v254, 1
	s_add_u32 s8, s68, 0x1e388000
	s_addc_u32 s9, s69, 0
	s_sub_i32 s4, s33, 64
	s_mov_b64 s[2:3], exec
	s_and_b64 s[0:1], s[2:3], s[0:1]
	s_mov_b64 exec, s[0:1]
	s_cbranch_execz .Lemb_w1
	v_mov_b32_e32 v3, 0
.Lemb_w0:
	global_load_dword v4, v3, s[8:9] sc1
	s_waitcnt vmcnt(0)
	v_cmp_gt_u32_e32 vcc, s4, v4
	s_cbranch_vccz .Lemb_w2
	s_sleep 1
	s_branch .Lemb_w0

.Lemb_w1:
	s_mov_b64 exec, s[2:3]
	s_barrier
	s_mov_b32 s98, 1
	s_sub_i32 s99, s93, 0x60
	s_branch .Lemb_entry
.Lemb_ret:
	s_cmp_lg_u32 s98, 1
	s_cbranch_scc1 .Lemb_done
	s_cmpk_gt_u32 s93, 0xbf
	s_cbranch_scc1 .Lemb_done
	s_mov_b32 s98, 2
	s_add_i32 s99, s93, 64
	s_branch .Lemb_entry
.Lemb_done:
	s_add_i32 s23, s66, 3
	s_branch .LBB0_369

.LBB0_407:
	s_cmp_lt_i32 s70, 5
	s_cselect_b64 s[0:1], -1, 0
	s_cmp_gt_i32 s71, 4
	s_cselect_b64 s[2:3], -1, 0
	s_and_b64 s[0:1], s[0:1], s[2:3]
	s_andn2_b64 vcc, exec, s[0:1]
	s_cbranch_vccnz .LBB0_461
	s_mov_b32 s98, 0
	s_add_i32 s99, s93, 0x100
.Lemb_entry:
	s_add_u32 s88, s68, 0xf200000
	s_addc_u32 s89, s69, 0
	s_cmpk_lt_i32 s99, 0x200
	s_cselect_b64 s[0:1], -1, 0
	s_cmpk_gt_i32 s99, 0x1ff
	v_readfirstlane_b32 s4, v186
	s_cbranch_scc1 .LBB0_414
	s_ashr_i32 s2, s99, 31
	s_lshr_b32 s2, s2, 29
	s_add_i32 s5, s99, s2
	s_and_b32 s2, s5, -8
	s_sub_i32 s6, s99, s2
	s_cmp_gt_i32 s6, -1
	s_cbranch_scc0 .LBB0_411
	s_lshl_b32 s7, s6, 6
	s_cbranch_execz .LBB0_412
	s_branch .LBB0_413

.LBB0_414:
	s_andn2_b64 vcc, exec, s[0:1]
	s_cbranch_vccnz .LBB0_450
	s_add_u32 s13, s68, 0x17200000
	s_addc_u32 s36, s69, 0
	v_lshlrev_b32_e32 v0, 4, v186
	s_add_u32 s37, s68, 0x800000
	v_and_b32_e32 v1, 32, v186
	v_bfe_u32 v10, v186, 2, 4
	v_lshrrev_b32_e32 v2, 3, v186
	s_movk_i32 s0, 0x70
	v_add_u32_e32 v11, 0x2000, v0
	s_addc_u32 s38, s69, 0
	v_bitop3_b32 v8, v0, v1, 48 bitop3:0x6c
	v_and_or_b32 v2, v2, s0, v10
	v_lshrrev_b32_e32 v0, 7, v11
	s_movk_i32 s0, 0xf0
	s_lshr_b32 s3, s4, 6
	s_ashr_i32 s23, s22, 31
	s_ashr_i32 s25, s24, 31
	s_lshr_b32 s2, s4, 8
	v_and_or_b32 v0, v0, s0, v10
	s_lshl_b32 s39, s3, 10
	s_lshl_b64 s[0:1], s[22:23], 19
	s_lshl_b64 s[6:7], s[24:25], 19
	v_and_b32_e32 v9, 64, v186
	s_add_u32 s28, s37, s6
	v_or_b32_e32 v1, v8, v9
	s_addc_u32 s29, s38, s7
	s_add_i32 s25, s39, 0
	v_lshl_or_b32 v128, v2, 11, v1
	s_add_i32 m0, s25, 0x10000
	v_lshl_or_b32 v130, v0, 11, v1
	global_load_lds_dwordx4 v128, s[28:29]
	s_add_i32 m0, s25, 0x12000
	s_add_u32 s6, s28, 0x40000
	global_load_lds_dwordx4 v130, s[28:29]
	s_addc_u32 s7, s29, 0
	s_add_i32 m0, s25, 0x14000
	v_mov_b32_e32 v129, 0
	global_load_lds_dwordx4 v128, s[6:7]
	s_add_i32 m0, s25, 0x16000
	s_add_u32 s26, s13, s0
	s_addc_u32 s27, s36, s1
	s_add_i32 s40, s25, 0x2000
	global_load_lds_dwordx4 v130, s[6:7]
	s_mov_b32 m0, s25
	s_add_u32 s0, s26, 0x40000
	global_load_lds_dwordx4 v128, s[26:27]
	s_mov_b32 m0, s40
	s_addc_u32 s1, s27, 0
	s_add_i32 s41, s25, 0x4000
	global_load_lds_dwordx4 v130, s[26:27]
	s_mov_b32 m0, s41
	s_add_i32 s42, s25, 0x6000
	global_load_lds_dwordx4 v128, s[0:1]
	s_mov_b32 m0, s42
	v_mov_b32_e32 v131, v129
	global_load_lds_dwordx4 v130, s[0:1]
	s_cmp_eq_u32 s2, 1
	s_mov_b32 s43, 1
	v_lshl_add_u64 v[6:7], s[28:29], 0, v[128:129]
	v_lshl_add_u64 v[4:5], s[28:29], 0, v[130:131]
	v_lshl_add_u64 v[0:1], s[26:27], 0, v[128:129]
	s_cselect_b64 s[0:1], -1, 0
	s_cmp_lg_u32 s2, 1
	v_lshl_add_u64 v[2:3], s[26:27], 0, v[130:131]
	s_cbranch_scc1 .LBB0_417
	s_barrier

.LBB0_449:
	s_waitcnt vmcnt(0)
	s_barrier
	s_cmp_lg_u32 s98, 0
	s_cbranch_scc1 .Lemb_ret

	.amdhsa_kernel _Z14fwd_megakernel4Args
		.amdhsa_group_segment_fixed_size 0
		.amdhsa_private_segment_fixed_size 0
		.amdhsa_kernarg_size 464
		.amdhsa_user_sgpr_count 2
		.amdhsa_user_sgpr_dispatch_ptr 0
		.amdhsa_user_sgpr_queue_ptr 0
		.amdhsa_user_sgpr_kernarg_segment_ptr 1
		.amdhsa_user_sgpr_dispatch_id 0
		.amdhsa_user_sgpr_kernarg_preload_length 0
		.amdhsa_user_sgpr_kernarg_preload_offset 0
		.amdhsa_user_sgpr_private_segment_size 0
		.amdhsa_uses_dynamic_stack 0
		.amdhsa_enable_private_segment 0
		.amdhsa_system_sgpr_workgroup_id_x 1
		.amdhsa_system_sgpr_workgroup_id_y 0
		.amdhsa_system_sgpr_workgroup_id_z 0
		.amdhsa_system_sgpr_workgroup_info 0
		.amdhsa_system_vgpr_workitem_id 2
		.amdhsa_next_free_vgpr 256
		.amdhsa_next_free_sgpr 100
		.amdhsa_accum_offset 256
		.amdhsa_reserve_vcc 1
		.amdhsa_float_round_mode_32 0
		.amdhsa_float_round_mode_16_64 0
		.amdhsa_float_denorm_mode_32 3
		.amdhsa_float_denorm_mode_16_64 3
		.amdhsa_dx10_clamp 1
		.amdhsa_ieee_mode 1
		.amdhsa_fp16_overflow 0
		.amdhsa_tg_split 0
		.amdhsa_exception_fp_ieee_invalid_op 0
		.amdhsa_exception_fp_denorm_src 0
		.amdhsa_exception_fp_ieee_div_zero 0
		.amdhsa_exception_fp_ieee_overflow 0
		.amdhsa_exception_fp_ieee_underflow 0
		.amdhsa_exception_fp_ieee_inexact 0
		.amdhsa_exception_int_div_zero 0
	.end_amdhsa_kernel

amdhsa.kernels:
  - .agpr_count:     0
    .args:
      - .offset:         0
        .size:           208
        .value_kind:     by_value
      - .offset:         208
        .size:           4
        .value_kind:     hidden_block_count_x
      - .offset:         212
        .size:           4
        .value_kind:     hidden_block_count_y
      - .offset:         216
        .size:           4
        .value_kind:     hidden_block_count_z
      - .offset:         220
        .size:           2
        .value_kind:     hidden_group_size_x
      - .offset:         222
        .size:           2
        .value_kind:     hidden_group_size_y
      - .offset:         224
        .size:           2
        .value_kind:     hidden_group_size_z
      - .offset:         226
        .size:           2
        .value_kind:     hidden_remainder_x
      - .offset:         228
        .size:           2
        .value_kind:     hidden_remainder_y
      - .offset:         230
        .size:           2
        .value_kind:     hidden_remainder_z
      - .offset:         248
        .size:           8
        .value_kind:     hidden_global_offset_x
      - .offset:         256
        .size:           8
        .value_kind:     hidden_global_offset_y
      - .offset:         264
        .size:           8
        .value_kind:     hidden_global_offset_z
      - .offset:         272
        .size:           2
        .value_kind:     hidden_grid_dims
      - .offset:         296
        .size:           8
        .value_kind:     hidden_multigrid_sync_arg
      - .offset:         328
        .size:           4
        .value_kind:     hidden_dynamic_lds_size
    .group_segment_fixed_size: 0
    .kernarg_segment_align: 8
    .kernarg_segment_size: 464
    .language:       OpenCL C
    .language_version:
      - 2
      - 0
    .max_flat_workgroup_size: 512
    .name:           _Z14fwd_megakernel4Args
    .private_segment_fixed_size: 0
    .sgpr_count:     106
    .sgpr_spill_count: 70
    .symbol:         _Z14fwd_megakernel4Args.kd
    .uniform_work_group_size: 1
    .uses_dynamic_stack: false
    .vgpr_count:     256
    .vgpr_spill_count: 0
    .wavefront_size: 64
